# prep phase: touch loads ahead of the gate rows, compression source rows and copy items
# baseline (speedup 1.0000x reference)
; DI void phase_prep(const Args& a, int layer, LAS unsigned char* lds) {
;     ...
;         for (int it = gw; it < 6 * 4 * 256; it += NGW) {
;             const int which = it / 1024, bg = (it / 256) & 3, st = it & 255, b = bg >> 1, g = bg & 1;
;             if (which >= 3) {
;                 const int srccol = (which == 3 ? C_KS : which == 4 ? C_KW : C_KB) + g * 64;
;                 bf16_t* dst = (bf16_t*)(ws + (which == 3 ? WS_KSF : which == 4 ? WS_KWF : WS_KBF)) + (size_t)bg * 64 * S + (size_t)st * 4096;
;                 float rmax = 0.f;
; #pragma unroll
;                 for (int i = 0; i < 8; ++i) { const int tok = i * 8 + (lane >> 3), q = lane & 7;
;                     const u32x4 v = *(const u32x4*)(P + (size_t)(b * S + st * 64 + tok) * NP + srccol + q * 8);
;     ...
;             const int srccol = (which == 0 ? C_VS : which == 1 ? C_VW : C_VB) + g * 64;
;             bf16_t* dst = (bf16_t*)(ws + (which == 0 ? WS_VST : which == 1 ? WS_VWT : WS_VBT)) + (size_t)bg * 64 * S + (size_t)st * 4096;
; #pragma unroll
;             for (int i = 0; i < 8; ++i) { const int tok = i * 8 + (lane >> 3), ch = lane & 7;
;                 const u32x4 v = *(const u32x4*)(P + (size_t)(b * S + st * 64 + tok) * NP + srccol + ch * 8);
.LBB0_340:
	s_and_b64 vcc, exec, s[0:1]
	s_cbranch_vccz .LBB0_406
	v_mov_b32_e32 v42, v185
	v_readlane_b32 s0, v252, 34
	v_ashrrev_i32_e32 v44, 6, v42
	v_and_b32_e32 v15, 31, v42
	v_add_u32_e32 v14, s0, v44
	s_movk_i32 s0, 0x17ff
	v_cmp_lt_i32_e32 vcc, s0, v14
	s_and_saveexec_b64 s[0:1], vcc
	s_xor_b64 s[0:1], exec, s[0:1]
	v_and_b32_e32 v128, 31, v42
	s_or_saveexec_b64 s[24:25], s[0:1]
	v_readlane_b32 s0, v252, 5
	v_readlane_b32 s1, v252, 6
	s_load_dword s19, s[0:1], 0x0
	v_and_b32_e32 v45, 63, v42
	v_lshlrev_b32_e32 v43, 5, v42
	s_waitcnt lgkmcnt(0)
	s_lshl_b32 s27, s19, 3
	s_xor_b64 exec, exec, s[24:25]
	s_cbranch_execz .LBB0_353
	s_movk_i32 s0, 0x2400
	v_lshrrev_b32_e32 v3, 3, v42
	v_mul_lo_u32 v0, v44, s0
	v_lshlrev_b32_e32 v1, 4, v42
	v_and_b32_e32 v18, 4, v3
	v_lshrrev_b32_e32 v3, 2, v42
	v_add_u32_e32 v16, 0, v0
	v_lshrrev_b32_e32 v17, 3, v45
	v_and_b32_e32 v128, 0x70, v1
	v_and_b32_e32 v20, 12, v3
	v_and_b32_e32 v3, 7, v42
	v_lshl_add_u64 v[4:5], s[30:31], 0, v[128:129]
	v_add_u32_e32 v2, v16, v128
	v_lshlrev_b32_e32 v128, 4, v3
	v_and_b32_e32 v3, 48, v1
	v_readlane_b32 s0, v255, 12
	v_or_b32_e32 v24, 24, v17
	s_waitcnt vmcnt(0)
	v_bitop3_b32 v37, v1, 48, 64 bitop3:0xe0
	s_lshl_b32 s8, s0, 4
	v_and_b32_e32 v9, 64, v1
	v_or_b32_e32 v1, v37, v17
	v_and_or_b32 v10, v24, 15, v3
	s_movk_i32 s0, 0x80
	v_and_b32_e32 v21, 0xe0, v43
	v_or_b32_e32 v28, 56, v17
	v_or_b32_e32 v39, 0x80, v1
	v_or3_b32 v41, v10, v9, s0
	v_bitop3_b32 v10, v17, 23, 48 bitop3:0xc8
	s_movk_i32 s0, 0x100
	v_or_b32_e32 v48, 0x180, v1
	v_bitop3_b32 v1, v17, 31, 56 bitop3:0xc8
	v_lshlrev_b32_e32 v0, 3, v45
	v_and_b32_e32 v19, 15, v42
	v_mul_u32_u24_e32 v8, 0x90, v17
	v_or_b32_e32 v23, 16, v17
	v_or3_b32 v47, v21, v10, s0
	v_or3_b32 v49, v21, v1, s0
	v_and_or_b32 v1, v28, 15, v3
	s_movk_i32 s0, 0x180
	v_lshl_add_u64 v[6:7], s[30:31], 0, v[128:129]
	v_cmp_eq_u32_e32 vcc, 0, v45
	s_add_i32 s8, s8, -12
	v_or_b32_e32 v22, 8, v17
	v_or_b32_e32 v25, 32, v17
	v_or_b32_e32 v26, 40, v17
	v_or_b32_e32 v27, 48, v17
	v_or_b32_e32 v29, 32, v15
	v_or_b32_e32 v30, 16, v19
	v_or_b32_e32 v31, 16, v18
	v_or_b32_e32 v32, 32, v19
	v_or_b32_e32 v33, 48, v19
	v_or_b32_e32 v34, 32, v18
	v_or_b32_e32 v35, 16, v20
	v_or_b32_e32 v36, 48, v18
	v_or_b32_e32 v38, v21, v23
	v_or_b32_e32 v40, v21, v24
	v_bitop3_b32 v46, v17, 15, 40 bitop3:0xc8
	v_or3_b32 v50, v1, v9, s0
	s_mov_b64 s[40:41], 0
	v_add_u32_e32 v51, v2, v8
	v_lshlrev_b32_e32 v8, 1, v0
	v_mov_b32_e32 v52, v14
	v_readlane_b32 s1, v255, 13
	v_readfirstlane_b32 s44, v14
	s_nop 1
	s_cmp_lt_u32 s44, 0x400
	s_movk_i32 s100, 0x13ff
	s_movk_i32 s101, 0x400
	s_cselect_b32 s100, 0x17ff, s100
	s_cselect_b32 s101, 0x1400, s101
	v_mbcnt_lo_u32_b32 v53, -1, 0
	v_mbcnt_hi_u32_b32 v53, -1, v53
	v_mul_u32_u24_e32 v53, 0x1a00, v53
.Lpt_loop:
	s_lshr_b32 s45, s44, 10
	s_bfe_u32 s46, s44, 0x20008
	s_and_b32 s47, s44, 0xff
	s_lshr_b32 s48, s46, 1
	s_and_b32 s46, s46, 1
	s_lshl_b32 s48, s48, 14
	s_lshl_b32 s47, s47, 6
	s_add_u32 s47, s47, s48
	s_mul_i32 s47, s47, 0x1a00
	s_lshl_b32 s46, s46, 7
	s_lshl_b32 s49, s45, 9
	s_add_u32 s46, s46, s49
	s_movk_i32 s49, 0xc00
	s_movk_i32 s50, 0x1300
	s_cmp_lt_u32 s45, 3
	s_cselect_b32 s49, s50, s49
	s_add_u32 s46, s46, s49
	s_add_u32 s47, s47, s46
	s_add_u32 s52, s98, s47
	s_addc_u32 s53, s99, 0
	s_add_u32 s52, s52, 0x30000000
	s_addc_u32 s53, s53, 0
	global_load_dword v184, v53, s[52:53]
	s_add_u32 s44, s44, s101
	s_cmp_le_u32 s44, s100
	s_cbranch_scc1 .Lpt_loop
	s_branch .LBB0_347

; #define MFMA32(a, b, c) __builtin_amdgcn_mfma_f32_32x32x16_bf16((a), (b), (c), 0, 0, 0)
; DI void phase_prep(const Args& a, int layer, LAS unsigned char* lds) {
;     ...
;         for (int it = NGW - 1 - gw; it < M / 32; it += NGW) {
;             const bf16_t* ar = XN + (size_t)(it * 32 + c) * D + hi * 8;
;             const bf16_t* b0 = wg + (size_t)c * D + hi * 8, *b1 = wg + (size_t)(32 + c) * D + hi * 8;
;             f32x16 a0, a1;
; #pragma unroll
;             for (int r = 0; r < 16; ++r) { a0[r] = 0.f; a1[r] = 0.f; }
; #pragma unroll 8
;             for (int kk = 0; kk < 128; ++kk) {
;                 const bf16x8 af = *(const bf16x8*)(ar + kk * 16);
;                 a0 = MFMA32(af, *(const bf16x8*)(b0 + kk * 16), a0);
;                 a1 = MFMA32(af, *(const bf16x8*)(b1 + kk * 16), a1);
.LBB0_357:
	s_waitcnt vmcnt(0)
	s_mov_b32 s38, 0x18000000
	s_mov_b32 s39, 0
	v_lshl_add_u64 v[110:111], v[40:41], 0, s[38:39]
	s_mov_b32 s38, 0xc00000
	v_lshl_add_u64 v[112:113], v[38:39], 0, s[38:39]
	s_mov_b32 s38, 0xc20000
	v_lshl_add_u64 v[114:115], v[38:39], 0, s[38:39]
	s_mov_b64 s[38:39], 0x100
	s_mov_b32 s8, 0
	v_mbcnt_lo_u32_b32 v103, -1, 0
	v_mbcnt_hi_u32_b32 v103, -1, v103
	v_lshrrev_b32_e32 v103, 5, v103
	v_lshlrev_b32_e32 v100, 7, v103
	v_mov_b32_e32 v101, 0
	v_lshl_add_u64 v[100:101], v[110:111], 0, v[100:101]
	global_load_dword v102, v[100:101], off
	global_load_dword v102, v[100:101], off offset:256
	global_load_dword v102, v[100:101], off offset:512
	global_load_dword v102, v[100:101], off offset:768
	global_load_dword v102, v[100:101], off offset:1024
	global_load_dword v102, v[100:101], off offset:1280
	global_load_dword v102, v[100:101], off offset:1536
	global_load_dword v102, v[100:101], off offset:1792
	global_load_dword v102, v[100:101], off offset:2048
	global_load_dword v102, v[100:101], off offset:2304
	global_load_dword v102, v[100:101], off offset:2560
	global_load_dword v102, v[100:101], off offset:2816
	global_load_dword v102, v[100:101], off offset:3072
	global_load_dword v102, v[100:101], off offset:3328
	global_load_dword v102, v[100:101], off offset:3584
	global_load_dword v102, v[100:101], off offset:3840

; #define MFMA32(a, b, c) __builtin_amdgcn_mfma_f32_32x32x16_bf16((a), (b), (c), 0, 0, 0)
; DI void phase_prep(const Args& a, int layer, LAS unsigned char* lds) {
;     ...
;             int irow = rt * 64 + rg * 32 + c; irow = irow > 1022 ? 1022 : irow;
;             const bf16_t* src = P + (size_t)(b * S + 16 * irow) * NP + (kv ? C_VC : C_KC) + g * 64;
;             const bf16_t* bsrc = w1t + (size_t)(nt * 32 + c) * 2048 + hi * 8;
;             f32x16 acc;
; #pragma unroll
;             for (int r = 0; r < 16; ++r) acc[r] = 0.f;
; #pragma unroll 4
;             for (int kk = 0; kk < 128; ++kk) {
;                 const int tok = kk >> 2, d = (kk & 3) * 16 + hi * 8;
;                 const u32x4 sv = *(const u32x4*)(src + (size_t)tok * NP + d);
;                 const f32x4 p0 = *(const f32x4*)(pos + tok * 64 + d), p1 = *(const f32x4*)(pos + tok * 64 + d + 4);
;                 const bf16x8 af = pack8(bflo(sv.x) + p0.x, bfhi(sv.x) + p0.y, bflo(sv.y) + p0.z, bfhi(sv.y) + p0.w,
;                                         bflo(sv.z) + p1.x, bfhi(sv.z) + p1.y, bflo(sv.w) + p1.z, bfhi(sv.w) + p1.w);
;                 const bf16x8 bf = *(const bf16x8*)(bsrc + kk * 16);
;                 acc = MFMA32(af, bf, acc);
;             }
.LBB0_395:
	s_waitcnt vmcnt(0)
	s_mov_b32 s47, 0
	s_mov_b32 s46, 0
	s_mov_b32 s17, 0
	s_mov_b32 s23, 0
	s_mov_b32 s8, 0
	v_lshl_add_u64 v[124:125], v[36:37], 0, s[46:47]
	v_mbcnt_lo_u32_b32 v16, -1, 0
	v_mbcnt_hi_u32_b32 v16, -1, v16
	v_lshrrev_b32_e32 v16, 5, v16
	v_mul_u32_u24_e32 v16, 0x1a00, v16
	v_mov_b32_e32 v17, 0
	v_lshl_add_u64 v[16:17], v[38:39], 0, v[16:17]
	s_mov_b32 s16, 0
	v_lshl_add_u64 v[18:19], v[16:17], 0, s[16:17]
	global_load_dword v20, v[18:19], off offset:-64
	s_add_u32 s16, s16, 0x3400
	v_lshl_add_u64 v[22:23], v[16:17], 0, s[16:17]
	global_load_dword v20, v[22:23], off offset:-64
	s_add_u32 s16, s16, 0x3400
	v_lshl_add_u64 v[18:19], v[16:17], 0, s[16:17]
	global_load_dword v20, v[18:19], off offset:-64
	s_add_u32 s16, s16, 0x3400
	v_lshl_add_u64 v[22:23], v[16:17], 0, s[16:17]
	global_load_dword v20, v[22:23], off offset:-64
	s_add_u32 s16, s16, 0x3400
	v_lshl_add_u64 v[18:19], v[16:17], 0, s[16:17]
	global_load_dword v20, v[18:19], off offset:-64
	s_add_u32 s16, s16, 0x3400
	v_lshl_add_u64 v[22:23], v[16:17], 0, s[16:17]
	global_load_dword v20, v[22:23], off offset:-64
	s_add_u32 s16, s16, 0x3400
	v_lshl_add_u64 v[18:19], v[16:17], 0, s[16:17]
	global_load_dword v20, v[18:19], off offset:-64
	s_add_u32 s16, s16, 0x3400
	v_lshl_add_u64 v[22:23], v[16:17], 0, s[16:17]
	global_load_dword v20, v[22:23], off offset:-64
	s_add_u32 s16, s16, 0x3400
	v_lshl_add_u64 v[18:19], v[16:17], 0, s[16:17]
	global_load_dword v20, v[18:19], off offset:-64
	s_add_u32 s16, s16, 0x3400
	v_lshl_add_u64 v[22:23], v[16:17], 0, s[16:17]
	global_load_dword v20, v[22:23], off offset:-64
	s_add_u32 s16, s16, 0x3400
	v_lshl_add_u64 v[18:19], v[16:17], 0, s[16:17]
	global_load_dword v20, v[18:19], off offset:-64
	s_add_u32 s16, s16, 0x3400
	v_lshl_add_u64 v[22:23], v[16:17], 0, s[16:17]
	global_load_dword v20, v[22:23], off offset:-64
	s_add_u32 s16, s16, 0x3400
	v_lshl_add_u64 v[18:19], v[16:17], 0, s[16:17]
	global_load_dword v20, v[18:19], off offset:-64
	s_add_u32 s16, s16, 0x3400
	v_lshl_add_u64 v[22:23], v[16:17], 0, s[16:17]
	global_load_dword v20, v[22:23], off offset:-64
	s_add_u32 s16, s16, 0x3400
	v_lshl_add_u64 v[18:19], v[16:17], 0, s[16:17]
	global_load_dword v20, v[18:19], off offset:-64
	s_add_u32 s16, s16, 0x3400
	v_lshl_add_u64 v[22:23], v[16:17], 0, s[16:17]
	global_load_dword v20, v[22:23], off offset:-64
	global_load_dwordx4 v[48:51], v[38:39], off offset:-64
	global_load_dwordx4 v[52:55], v[124:125], off
	global_load_dwordx4 v[56:59], v[124:125], off offset:16
	global_load_dwordx4 v[60:63], v[40:41], off offset:-64
	global_load_dwordx4 v[64:67], v[38:39], off offset:-32
	global_load_dwordx4 v[68:71], v[124:125], off offset:64
	global_load_dwordx4 v[72:75], v[124:125], off offset:80
	global_load_dwordx4 v[76:79], v[40:41], off offset:-32
	global_load_dwordx4 v[80:83], v[38:39], off offset:0
	global_load_dwordx4 v[84:87], v[124:125], off offset:128
	global_load_dwordx4 v[88:91], v[124:125], off offset:144
	global_load_dwordx4 v[92:95], v[40:41], off offset:0
	global_load_dwordx4 v[96:99], v[38:39], off offset:32
	global_load_dwordx4 v[100:103], v[124:125], off offset:192
	global_load_dwordx4 v[104:107], v[124:125], off offset:208
	global_load_dwordx4 v[108:111], v[40:41], off offset:32
